# ECONV row loads nt as well (loads only), on top of ERES + PRO nt loads
# baseline (speedup 1.0000x reference)
.LBB0_51:
	s_or_b64 exec, exec, s[38:39]
	v_add_u32_e32 v26, 2, v127
	v_ashrrev_i32_e32 v27, 31, v26
	v_lshlrev_b64 v[110:111], 11, v[26:27]
	v_lshl_add_u64 v[26:27], v[58:59], 0, v[110:111]
	global_load_dwordx4 v[102:105], v[26:27], off nt
	v_lshl_add_u64 v[26:27], v[60:61], 0, v[110:111]
	global_load_dwordx4 v[118:121], v[26:27], off nt
	v_add_u32_e32 v26, 3, v127
	v_ashrrev_i32_e32 v27, 31, v26
	v_lshlrev_b64 v[90:91], 11, v[26:27]
	v_lshl_add_u64 v[26:27], v[58:59], 0, v[90:91]
	global_load_dwordx4 v[46:49], v[26:27], off nt
	v_lshl_add_u64 v[26:27], v[60:61], 0, v[90:91]
	global_load_dwordx4 v[50:53], v[26:27], off nt
	v_add_u32_e32 v26, 4, v127
	v_ashrrev_i32_e32 v27, 31, v26
	v_lshlrev_b64 v[92:93], 11, v[26:27]
	v_lshl_add_u64 v[26:27], v[58:59], 0, v[92:93]
	v_lshl_add_u64 v[30:31], v[60:61], 0, v[92:93]
	global_load_dwordx4 v[26:29], v[26:27], off nt
	global_load_dwordx4 v[42:45], v[30:31], off nt
	v_add_u32_e32 v30, 5, v127
	v_ashrrev_i32_e32 v31, 31, v30
	v_lshlrev_b64 v[88:89], 11, v[30:31]
	v_lshl_add_u64 v[30:31], v[58:59], 0, v[88:89]
	global_load_dwordx4 v[30:33], v[30:31], off nt
	v_lshl_add_u64 v[34:35], v[60:61], 0, v[88:89]
	global_load_dwordx4 v[34:37], v[34:35], off nt
	s_waitcnt vmcnt(8)
	v_lshlrev_b32_e32 v94, 16, v54
	v_and_b32_e32 v96, 0xffff0000, v54
	v_lshlrev_b32_e32 v100, 16, v55
	v_and_b32_e32 v98, 0xffff0000, v55
	v_lshlrev_b32_e32 v54, 16, v56
	v_lshlrev_b32_e32 v106, 16, v57
	v_add_u32_e32 v126, s2, v126
	s_movk_i32 s15, 0x2003
	v_cmp_lt_i32_e32 vcc, s15, v126
	v_add_u32_e32 v127, s6, v127
	s_or_b64 s[42:43], vcc, s[42:43]
	s_waitcnt vmcnt(7)
	v_lshlrev_b32_e32 v95, 16, v102
	v_pk_mul_f32 v[124:125], v[76:77], v[94:95]
	v_and_b32_e32 v97, 0xffff0000, v102
	v_lshlrev_b32_e32 v101, 16, v103
	v_lshlrev_b32_e32 v55, 16, v104
	v_and_b32_e32 v102, 0xffff0000, v56
	v_lshlrev_b32_e32 v107, 16, v105
	v_lshlrev_b32_e32 v56, 16, v38
	s_waitcnt vmcnt(6)
	v_lshlrev_b32_e32 v0, 16, v118
	v_and_b32_e32 v94, 0xffff0000, v118
	v_lshlrev_b32_e32 v130, 16, v119
	v_pk_mul_f32 v[108:109], v[72:73], v[100:101]
	v_and_b32_e32 v100, 0xffff0000, v119
	v_lshlrev_b32_e32 v131, 16, v120
	v_pk_mul_f32 v[114:115], v[68:69], v[54:55]
	v_and_b32_e32 v54, 0xffff0000, v120
	v_lshlrev_b32_e32 v132, 16, v121
	v_pk_mul_f32 v[118:119], v[64:65], v[106:107]
	v_and_b32_e32 v106, 0xffff0000, v121
	v_lshl_add_u64 v[120:121], v[62:63], 0, v[110:111]
	v_fma_f32 v110, v22, v56, v124
	v_and_b32_e32 v99, 0xffff0000, v103
	v_and_b32_e32 v103, 0xffff0000, v104
	v_and_b32_e32 v104, 0xffff0000, v57
	s_waitcnt vmcnt(5)
	v_lshlrev_b32_e32 v57, 16, v46
	v_add_f32_e32 v110, v110, v125
	v_mul_f32_e32 v0, v110, v0
	v_pk_mul_f32 v[110:111], v[76:77], v[56:57]
	v_pk_mul_f32 v[128:129], v[78:79], v[96:97]
	v_fma_f32 v56, v22, v95, v110
	v_and_b32_e32 v110, 0xffff0000, v38
	v_fma_f32 v38, v23, v110, v128
	v_add_f32_e32 v56, v56, v111
	v_and_b32_e32 v111, 0xffff0000, v46
	v_add_f32_e32 v38, v38, v129
	v_mul_f32_e32 v38, v38, v94
	v_pk_mul_f32 v[124:125], v[78:79], v[110:111]
	v_cvt_pk_bf16_f32 v38, v0, v38
	s_waitcnt vmcnt(4)
	v_lshlrev_b32_e32 v133, 16, v50
	v_fma_f32 v0, v23, v97, v124
	v_and_b32_e32 v50, 0xffff0000, v50
	v_add_f32_e32 v0, v0, v125
	v_lshlrev_b32_e32 v124, 16, v39
	v_mul_f32_e32 v0, v0, v50
	v_lshlrev_b32_e32 v125, 16, v47
	v_fma_f32 v50, v24, v124, v108
	v_add_f32_e32 v50, v50, v109
	v_pk_mul_f32 v[108:109], v[72:73], v[124:125]
	v_lshlrev_b32_e32 v46, 16, v51
	v_fma_f32 v94, v24, v101, v108
	v_add_f32_e32 v94, v94, v109
	v_pk_mul_f32 v[112:113], v[74:75], v[98:99]
	v_mul_f32_e32 v94, v94, v46
	v_and_b32_e32 v46, 0xffff0000, v39
	v_fma_f32 v39, v25, v46, v112
	v_add_f32_e32 v39, v39, v113
	v_mul_f32_e32 v50, v50, v130
	v_and_b32_e32 v47, 0xffff0000, v47
	v_mul_f32_e32 v39, v39, v100
	v_and_b32_e32 v108, 0xffff0000, v51
	v_cvt_pk_bf16_f32 v39, v50, v39
	v_pk_mul_f32 v[50:51], v[74:75], v[46:47]
	v_lshlrev_b32_e32 v100, 16, v52
	v_fma_f32 v46, v25, v99, v50
	v_add_f32_e32 v46, v46, v51
	v_lshlrev_b32_e32 v50, 16, v40
	v_mul_f32_e32 v46, v46, v108
	v_fma_f32 v108, v18, v50, v114
	v_lshlrev_b32_e32 v51, 16, v48
	v_add_f32_e32 v108, v108, v115
	v_mul_f32_e32 v110, v108, v131
	v_pk_mul_f32 v[108:109], v[68:69], v[50:51]
	v_and_b32_e32 v52, 0xffff0000, v52
	v_fma_f32 v50, v18, v55, v108
	v_add_f32_e32 v50, v50, v109
	v_and_b32_e32 v109, 0xffff0000, v48
	v_and_b32_e32 v108, 0xffff0000, v40
	v_pk_mul_f32 v[112:113], v[70:71], v[108:109]
	v_mul_f32_e32 v50, v50, v100
	v_fma_f32 v48, v19, v103, v112
	v_add_f32_e32 v48, v48, v113
	v_lshlrev_b32_e32 v112, 16, v41
	v_lshlrev_b32_e32 v113, 16, v49
	v_pk_mul_f32 v[114:115], v[64:65], v[112:113]
	v_pk_mul_f32 v[116:117], v[70:71], v[102:103]
	v_fma_f32 v100, v20, v107, v114
	v_and_b32_e32 v105, 0xffff0000, v105
	v_mul_f32_e32 v52, v48, v52
	v_lshlrev_b32_e32 v48, 16, v53
	v_add_f32_e32 v100, v100, v115
	v_pk_mul_f32 v[122:123], v[66:67], v[104:105]
	v_fma_f32 v40, v19, v108, v116
	v_mul_f32_e32 v100, v100, v48
	v_and_b32_e32 v48, 0xffff0000, v41
	v_add_f32_e32 v40, v40, v117
	v_fma_f32 v41, v21, v48, v122
	v_mul_f32_e32 v40, v40, v54
	v_fma_f32 v54, v20, v112, v118
	v_add_f32_e32 v41, v41, v123
	v_add_f32_e32 v54, v54, v119
	v_and_b32_e32 v49, 0xffff0000, v49
	v_mul_f32_e32 v41, v41, v106
	v_cvt_pk_bf16_f32 v40, v110, v40
	v_mul_f32_e32 v54, v54, v132
	v_cvt_pk_bf16_f32 v41, v54, v41
	global_store_dwordx4 v[120:121], v[38:41], off
	v_and_b32_e32 v53, 0xffff0000, v53
	v_mul_f32_e32 v56, v56, v133
	v_pk_mul_f32 v[38:39], v[66:67], v[48:49]
	v_cvt_pk_bf16_f32 v40, v50, v52
	s_waitcnt vmcnt(3)
	v_lshlrev_b32_e32 v48, 16, v43
	v_fma_f32 v38, v21, v105, v38
	v_add_f32_e32 v38, v38, v39
	v_mul_f32_e32 v41, v38, v53
	v_cvt_pk_bf16_f32 v41, v100, v41
	v_lshl_add_u64 v[52:53], v[62:63], 0, v[90:91]
	v_cvt_pk_bf16_f32 v38, v56, v0
	v_cvt_pk_bf16_f32 v39, v94, v46
	global_store_dwordx4 v[52:53], v[38:41], off
	v_lshlrev_b32_e32 v0, 16, v42
	v_and_b32_e32 v46, 0xffff0000, v42
	v_lshlrev_b32_e32 v40, 16, v26
	s_waitcnt vmcnt(3)
	v_lshlrev_b32_e32 v41, 16, v30
	v_and_b32_e32 v50, 0xffff0000, v43
	v_pk_mov_b32 v[42:43], v[94:95], v[40:41] op_sel:[1,0]
	v_pk_mul_f32 v[40:41], v[86:87], v[40:41]
	v_pk_mul_f32 v[42:43], v[76:77], v[42:43]
	v_fma_f32 v40, v6, v57, v40
	s_waitcnt vmcnt(2)
	v_lshlrev_b32_e32 v54, 16, v34
	v_fma_f32 v42, v22, v57, v42
	v_add_f32_e32 v40, v40, v41
	v_add_f32_e32 v42, v42, v43
	v_mul_f32_e32 v54, v40, v54
	v_and_b32_e32 v41, 0xffff0000, v30
	v_and_b32_e32 v40, 0xffff0000, v26
	v_mul_f32_e32 v0, v42, v0
	v_pk_mov_b32 v[42:43], v[96:97], v[40:41] op_sel:[1,0]
	v_pk_mul_f32 v[40:41], v[14:15], v[40:41]
	v_pk_mul_f32 v[42:43], v[78:79], v[42:43]
	v_and_b32_e32 v34, 0xffff0000, v34
	v_fma_f32 v26, v23, v111, v42
	v_add_f32_e32 v26, v26, v43
	v_mul_f32_e32 v26, v26, v46
	v_cvt_pk_bf16_f32 v26, v0, v26
	v_fma_f32 v0, v7, v111, v40
	v_add_f32_e32 v0, v0, v41
	v_lshlrev_b32_e32 v40, 16, v27
	v_lshlrev_b32_e32 v41, 16, v31
	v_pk_mov_b32 v[42:43], v[100:101], v[40:41] op_sel:[1,0]
	v_mul_f32_e32 v0, v0, v34
	v_pk_mul_f32 v[42:43], v[72:73], v[42:43]
	v_pk_mul_f32 v[40:41], v[84:85], v[40:41]
	v_fma_f32 v34, v24, v125, v42
	v_add_f32_e32 v34, v34, v43
	v_mul_f32_e32 v42, v34, v48
	v_fma_f32 v34, v8, v125, v40
	v_lshlrev_b32_e32 v30, 16, v35
	v_add_f32_e32 v34, v34, v41
	v_mul_f32_e32 v40, v34, v30
	v_and_b32_e32 v31, 0xffff0000, v31
	v_and_b32_e32 v30, 0xffff0000, v27
	v_and_b32_e32 v41, 0xffff0000, v35
	v_pk_mov_b32 v[34:35], v[98:99], v[30:31] op_sel:[1,0]
	v_pk_mul_f32 v[30:31], v[16:17], v[30:31]
	v_pk_mul_f32 v[34:35], v[74:75], v[34:35]
	v_fma_f32 v30, v9, v47, v30
	v_add_f32_e32 v30, v30, v31
	v_fma_f32 v27, v25, v47, v34
	v_mul_f32_e32 v41, v30, v41
	v_lshlrev_b32_e32 v30, 16, v28
	v_lshlrev_b32_e32 v31, 16, v32
	v_add_f32_e32 v27, v27, v35
	v_pk_mov_b32 v[34:35], v[54:55], v[30:31] op_sel:[1,0]
	v_pk_mul_f32 v[30:31], v[82:83], v[30:31]
	v_mul_f32_e32 v27, v27, v50
	v_pk_mul_f32 v[34:35], v[68:69], v[34:35]
	v_fma_f32 v30, v2, v51, v30
	v_cvt_pk_bf16_f32 v27, v42, v27
	v_lshlrev_b32_e32 v42, 16, v36
	v_fma_f32 v34, v18, v51, v34
	v_add_f32_e32 v30, v30, v31
	v_lshlrev_b32_e32 v52, 16, v44
	v_add_f32_e32 v34, v34, v35
	v_mul_f32_e32 v42, v30, v42
	v_and_b32_e32 v31, 0xffff0000, v32
	v_and_b32_e32 v30, 0xffff0000, v28
	v_mul_f32_e32 v43, v34, v52
	v_pk_mov_b32 v[34:35], v[102:103], v[30:31] op_sel:[1,0]
	v_pk_mul_f32 v[30:31], v[10:11], v[30:31]
	v_and_b32_e32 v36, 0xffff0000, v36
	v_fma_f32 v30, v3, v109, v30
	v_pk_mul_f32 v[34:35], v[70:71], v[34:35]
	v_add_f32_e32 v30, v30, v31
	v_fma_f32 v28, v19, v109, v34
	v_mul_f32_e32 v36, v30, v36
	v_lshlrev_b32_e32 v30, 16, v29
	v_lshlrev_b32_e32 v31, 16, v33
	v_add_f32_e32 v28, v28, v35
	v_pk_mov_b32 v[34:35], v[106:107], v[30:31] op_sel:[1,0]
	v_pk_mul_f32 v[30:31], v[80:81], v[30:31]
	v_pk_mul_f32 v[34:35], v[64:65], v[34:35]
	v_fma_f32 v30, v4, v113, v30
	v_lshlrev_b32_e32 v32, 16, v37
	v_fma_f32 v34, v20, v113, v34
	v_add_f32_e32 v30, v30, v31
	v_add_f32_e32 v34, v34, v35
	v_mul_f32_e32 v35, v30, v32
	v_and_b32_e32 v31, 0xffff0000, v33
	v_and_b32_e32 v30, 0xffff0000, v29
	v_pk_mov_b32 v[32:33], v[104:105], v[30:31] op_sel:[1,0]
	v_and_b32_e32 v44, 0xffff0000, v44
	v_pk_mul_f32 v[32:33], v[66:67], v[32:33]
	v_lshlrev_b32_e32 v53, 16, v45
	v_fma_f32 v29, v21, v49, v32
	v_and_b32_e32 v45, 0xffff0000, v45
	v_add_f32_e32 v29, v29, v33
	v_lshl_add_u64 v[38:39], v[62:63], 0, v[92:93]
	v_mul_f32_e32 v28, v28, v44
	v_mul_f32_e32 v29, v29, v45
	v_cvt_pk_bf16_f32 v28, v43, v28
	v_mul_f32_e32 v34, v34, v53
	v_cvt_pk_bf16_f32 v29, v34, v29
	global_store_dwordx4 v[38:39], v[26:29], off
	v_and_b32_e32 v37, 0xffff0000, v37
	s_nop 0
	v_pk_mul_f32 v[26:27], v[12:13], v[30:31]
	v_lshl_add_u64 v[30:31], v[62:63], 0, v[88:89]
	v_fma_f32 v26, v5, v49, v26
	v_add_f32_e32 v26, v26, v27
	v_mul_f32_e32 v29, v26, v37
	v_cvt_pk_bf16_f32 v26, v54, v0
	v_cvt_pk_bf16_f32 v27, v40, v41
	v_cvt_pk_bf16_f32 v28, v42, v36
	v_cvt_pk_bf16_f32 v29, v35, v29
	global_store_dwordx4 v[30:31], v[26:29], off
	s_andn2_b64 exec, exec, s[42:43]
	s_cbranch_execz .LBB0_64
